# w_up activation epilogue: conv weights of the second row half loaded with the first half's second group (no store-draining wait at the start of the second half)
# baseline (speedup 1.0000x reference)
.LBB0_378:
	v_mov_b32_e32 v184, v149
	v_mov_b32_e32 v185, v150
	v_mov_b32_e32 v149, v151
	v_pk_add_f32 v[148:149], v[184:185], v[148:149]
	v_cmp_eq_u32_e64 s[8:9], 0, v212
	v_add_f32_e32 v148, v148, v149
	v_fmamk_f32 v148, v148, 0x3a800000, v241
	v_rsq_f32_e32 v226, v148
	v_mov_b32_e32 v148, v145
	v_mov_b32_e32 v149, v146
	v_mov_b32_e32 v145, v147
	v_pk_add_f32 v[144:145], v[148:149], v[144:145]
	s_nop 0
	v_add_f32_e32 v144, v144, v145
	v_fmamk_f32 v144, v144, 0x3a800000, v241
	v_rsq_f32_e32 v224, v144
	v_mov_b32_e32 v144, v153
	v_mov_b32_e32 v145, v154
	v_mov_b32_e32 v153, v155
	v_pk_add_f32 v[144:145], v[144:145], v[152:153]
	s_nop 0
	v_add_f32_e32 v144, v144, v145
	v_fmamk_f32 v144, v144, 0x3a800000, v241
	v_rsq_f32_e32 v222, v144
	v_pk_mul_f32 v[144:145], v[140:141], v[226:227] op_sel_hi:[1,0]
	v_pk_mul_f32 v[140:141], v[128:129], v[226:227] op_sel_hi:[1,0]
	v_pk_mul_f32 v[128:129], v[136:137], v[224:225] op_sel_hi:[1,0]
	v_pk_mul_f32 v[136:137], v[126:127], v[224:225] op_sel_hi:[1,0]
	v_pk_mul_f32 v[126:127], v[134:135], v[222:223] op_sel_hi:[1,0]
	v_pk_mul_f32 v[134:135], v[132:133], v[222:223] op_sel_hi:[1,0]
	v_mov_b32_e32 v132, v218
	v_mov_b32_e32 v133, v218
	v_mov_b32_e32 v219, v218
	v_pk_mul_f32 v[118:119], v[118:119], v[132:133]
	s_waitcnt vmcnt(2)
	v_cndmask_b32_e64 v132, v172, v176, s[8:9]
	v_cndmask_b32_e64 v133, v173, v177, s[8:9]
	v_mov_b32_dpp v148, v144 row_ror:1 row_mask:0xf bank_mask:0xf
	v_mov_b32_dpp v149, v145 row_ror:1 row_mask:0xf bank_mask:0xf
	v_mov_b32_dpp v150, v144 row_ror:2 row_mask:0xf bank_mask:0xf
	v_mov_b32_dpp v151, v145 row_ror:2 row_mask:0xf bank_mask:0xf
	v_cmp_lt_u32_e64 s[10:11], 1, v212
	v_pk_mul_f32 v[146:147], v[142:143], v[226:227] op_sel_hi:[1,0]
	v_pk_mul_f32 v[142:143], v[130:131], v[226:227] op_sel_hi:[1,0]
	v_pk_mul_f32 v[130:131], v[138:139], v[224:225] op_sel_hi:[1,0]
	v_pk_mul_f32 v[138:139], v[116:117], v[218:219]
	v_cndmask_b32_e64 v117, v149, v173, s[8:9]
	v_cndmask_b32_e64 v116, v148, v172, s[8:9]
	v_cndmask_b32_e64 v133, v133, v151, s[10:11]
	v_cndmask_b32_e64 v132, v132, v150, s[10:11]
	v_pk_mul_f32 v[132:133], v[156:157], v[132:133]
	v_mov_b32_dpp v172, v128 row_ror:2 row_mask:0xf bank_mask:0xf
	v_mov_b32_dpp v173, v129 row_ror:2 row_mask:0xf bank_mask:0xf
	s_waitcnt vmcnt(1)
	v_pk_fma_f32 v[116:117], v[160:161], v[116:117], v[132:133]
	v_mov_b32_dpp v154, v128 row_ror:1 row_mask:0xf bank_mask:0xf
	v_mov_b32_dpp v155, v129 row_ror:1 row_mask:0xf bank_mask:0xf
	v_cndmask_b32_e64 v151, v151, v173, s[10:11]
	v_cndmask_b32_e64 v150, v150, v172, s[10:11]
	s_waitcnt vmcnt(0)
	v_pk_fma_f32 v[116:117], v[144:145], v[164:165], v[116:117]
	v_cndmask_b32_e64 v149, v155, v149, s[8:9]
	v_cndmask_b32_e64 v148, v154, v148, s[8:9]
	v_pk_mul_f32 v[150:151], v[156:157], v[150:151]
	v_pk_mul_f32 v[132:133], v[116:117], s[56:57] op_sel_hi:[1,0]
	v_pk_fma_f32 v[148:149], v[160:161], v[148:149], v[150:151]
	v_exp_f32_e32 v132, v132
	v_exp_f32_e32 v133, v133
	v_pk_fma_f32 v[148:149], v[128:129], v[164:165], v[148:149]
	v_pk_mul_f32 v[124:125], v[124:125], v[224:225] op_sel_hi:[1,0]
	v_pk_mul_f32 v[150:151], v[148:149], s[56:57] op_sel_hi:[1,0]
	v_pk_add_f32 v[132:133], v[132:133], 1.0 op_sel_hi:[1,0]
	v_exp_f32_e32 v150, v150
	v_exp_f32_e32 v151, v151
	v_rcp_f32_e32 v132, v132
	v_rcp_f32_e32 v133, v133
	v_cndmask_b32_e64 v152, v169, v181, s[8:9]
	v_pk_add_f32 v[150:151], v[150:151], 1.0 op_sel_hi:[1,0]
	v_cndmask_b32_e64 v153, v168, v180, s[8:9]
	v_rcp_f32_e32 v150, v150
	v_rcp_f32_e32 v151, v151
	v_pk_mul_f32 v[116:117], v[116:117], v[132:133]
	v_cndmask_b32_e64 v133, v153, v172, s[6:7]
	v_pk_mul_f32 v[116:117], v[140:141], v[116:117]
	s_nop 0
	v_cvt_pk_bf16_f32 v132, v116, v117
	v_pk_mul_f32 v[116:117], v[148:149], v[150:151]
	v_cndmask_b32_e64 v148, v152, v173, s[6:7]
	v_pk_mul_f32 v[116:117], v[124:125], v[116:117]
	s_nop 0
	v_cvt_pk_bf16_f32 v116, v116, v117
	v_cndmask_b32_e64 v117, v168, v154, s[6:7]
	v_cndmask_b32_e64 v124, v169, v155, s[6:7]
	v_mov_b32_dpp v150, v134 row_ror:1 row_mask:0xf bank_mask:0xf
	v_mov_b32_dpp v151, v135 row_ror:1 row_mask:0xf bank_mask:0xf
	v_mov_b32_dpp v152, v134 row_ror:2 row_mask:0xf bank_mask:0xf
	v_mov_b32_dpp v153, v135 row_ror:2 row_mask:0xf bank_mask:0xf
	v_cndmask_b32_e64 v125, v151, v124, s[8:9]
	v_cndmask_b32_e64 v124, v150, v117, s[8:9]
	v_cndmask_b32_e64 v149, v148, v153, s[10:11]
	v_cndmask_b32_e64 v148, v133, v152, s[10:11]
	v_pk_mul_f32 v[148:149], v[156:157], v[148:149]
	v_mov_b32_dpp v117, v108 row_ror:1 row_mask:0xf bank_mask:0xf
	v_mov_b32_dpp v133, v109 row_ror:1 row_mask:0xf bank_mask:0xf
	v_mov_b32_dpp v154, v108 row_ror:2 row_mask:0xf bank_mask:0xf
	v_mov_b32_dpp v155, v109 row_ror:2 row_mask:0xf bank_mask:0xf
	v_pk_fma_f32 v[124:125], v[160:161], v[124:125], v[148:149]
	v_cndmask_b32_e64 v149, v133, v151, s[8:9]
	v_cndmask_b32_e64 v148, v117, v150, s[8:9]
	v_cndmask_b32_e64 v151, v153, v155, s[10:11]
	v_cndmask_b32_e64 v150, v152, v154, s[10:11]
	v_pk_fma_f32 v[124:125], v[134:135], v[164:165], v[124:125]
	v_pk_mul_f32 v[150:151], v[156:157], v[150:151]
	v_pk_mul_f32 v[134:135], v[124:125], s[56:57] op_sel_hi:[1,0]
	v_pk_fma_f32 v[148:149], v[160:161], v[148:149], v[150:151]
	v_exp_f32_e32 v134, v134
	v_exp_f32_e32 v135, v135
	v_pk_fma_f32 v[148:149], v[108:109], v[164:165], v[148:149]
	v_pk_mul_f32 v[120:121], v[120:121], v[222:223] op_sel_hi:[1,0]
	v_pk_mul_f32 v[150:151], v[148:149], s[56:57] op_sel_hi:[1,0]
	v_pk_add_f32 v[134:135], v[134:135], 1.0 op_sel_hi:[1,0]
	v_exp_f32_e32 v150, v150
	v_exp_f32_e32 v151, v151
	v_rcp_f32_e32 v134, v134
	v_rcp_f32_e32 v135, v135
	v_cndmask_b32_e64 v117, v174, v178, s[8:9]
	v_pk_add_f32 v[150:151], v[150:151], 1.0 op_sel_hi:[1,0]
	s_nop 0
	v_rcp_f32_e32 v150, v150
	v_rcp_f32_e32 v151, v151
	v_pk_mul_f32 v[124:125], v[124:125], v[134:135]
	v_mov_b32_dpp v133, v146 row_ror:1 row_mask:0xf bank_mask:0xf
	v_pk_mul_f32 v[120:121], v[120:121], v[124:125]
	s_nop 0
	v_cvt_pk_bf16_f32 v124, v120, v121
	v_pk_mul_f32 v[120:121], v[148:149], v[150:151]
	s_nop 0
	v_pk_mul_f32 v[120:121], v[138:139], v[120:121]
	s_nop 0
	v_cvt_pk_bf16_f32 v120, v120, v121
	v_cndmask_b32_e64 v121, v175, v179, s[8:9]
	v_mov_b32_dpp v150, v146 row_ror:2 row_mask:0xf bank_mask:0xf
	v_mov_b32_dpp v151, v147 row_ror:2 row_mask:0xf bank_mask:0xf
	v_mov_b32_dpp v148, v147 row_ror:1 row_mask:0xf bank_mask:0xf
	v_cndmask_b32_e64 v139, v121, v151, s[10:11]
	v_cndmask_b32_e64 v138, v117, v150, s[10:11]
	v_cndmask_b32_e64 v135, v148, v175, s[8:9]
	v_cndmask_b32_e64 v134, v133, v174, s[8:9]
	v_pk_mul_f32 v[138:139], v[158:159], v[138:139]
	v_mov_b32_dpp v154, v130 row_ror:2 row_mask:0xf bank_mask:0xf
	v_mov_b32_dpp v155, v131 row_ror:2 row_mask:0xf bank_mask:0xf
	v_pk_fma_f32 v[134:135], v[162:163], v[134:135], v[138:139]
	v_mov_b32_dpp v121, v130 row_ror:1 row_mask:0xf bank_mask:0xf
	v_mov_b32_dpp v153, v131 row_ror:1 row_mask:0xf bank_mask:0xf
	v_cndmask_b32_e64 v151, v151, v155, s[10:11]
	v_cndmask_b32_e64 v150, v150, v154, s[10:11]
	v_pk_fma_f32 v[134:135], v[146:147], v[166:167], v[134:135]
	v_cndmask_b32_e64 v149, v153, v148, s[8:9]
	v_cndmask_b32_e64 v148, v121, v133, s[8:9]
	v_pk_mul_f32 v[150:151], v[158:159], v[150:151]
	v_pk_mul_f32 v[138:139], v[134:135], s[56:57] op_sel_hi:[1,0]
	v_pk_fma_f32 v[148:149], v[162:163], v[148:149], v[150:151]
	v_exp_f32_e32 v138, v138
	v_exp_f32_e32 v139, v139
	v_pk_fma_f32 v[148:149], v[130:131], v[166:167], v[148:149]
	v_cndmask_b32_e64 v125, v171, v183, s[8:9]
	v_pk_mul_f32 v[150:151], v[148:149], s[56:57] op_sel_hi:[1,0]
	v_pk_add_f32 v[138:139], v[138:139], 1.0 op_sel_hi:[1,0]
	v_exp_f32_e32 v150, v150
	v_exp_f32_e32 v151, v151
	v_rcp_f32_e32 v138, v138
	v_rcp_f32_e32 v139, v139
	v_cndmask_b32_e64 v152, v170, v182, s[8:9]
	v_pk_add_f32 v[150:151], v[150:151], 1.0 op_sel_hi:[1,0]
	v_cndmask_b32_e64 v121, v170, v121, s[6:7]
	v_rcp_f32_e32 v150, v150
	v_rcp_f32_e32 v151, v151
	v_pk_mul_f32 v[134:135], v[134:135], v[138:139]
	s_nop 0
	v_pk_mul_f32 v[134:135], v[142:143], v[134:135]
	s_nop 0
	v_cvt_pk_bf16_f32 v133, v134, v135
	v_pk_mul_f32 v[134:135], v[148:149], v[150:151]
	s_nop 0
	v_pk_mul_f32 v[134:135], v[136:137], v[134:135]
	s_nop 0
	v_cvt_pk_bf16_f32 v117, v134, v135
	v_cndmask_b32_e64 v134, v171, v153, s[6:7]
	v_cndmask_b32_e64 v136, v152, v154, s[6:7]
	v_cndmask_b32_e64 v125, v125, v155, s[6:7]
	v_mov_b32_dpp v138, v126 row_ror:1 row_mask:0xf bank_mask:0xf
	v_mov_b32_dpp v139, v127 row_ror:1 row_mask:0xf bank_mask:0xf
	v_mov_b32_dpp v148, v126 row_ror:2 row_mask:0xf bank_mask:0xf
	v_mov_b32_dpp v149, v127 row_ror:2 row_mask:0xf bank_mask:0xf
	v_cndmask_b32_e64 v135, v139, v134, s[8:9]
	v_cndmask_b32_e64 v134, v138, v121, s[8:9]
	v_cndmask_b32_e64 v137, v125, v149, s[10:11]
	v_cndmask_b32_e64 v136, v136, v148, s[10:11]
	v_pk_mul_f32 v[136:137], v[158:159], v[136:137]
	v_mov_b32_dpp v121, v110 row_ror:1 row_mask:0xf bank_mask:0xf
	v_mov_b32_dpp v125, v111 row_ror:1 row_mask:0xf bank_mask:0xf
	v_mov_b32_dpp v150, v110 row_ror:2 row_mask:0xf bank_mask:0xf
	v_mov_b32_dpp v151, v111 row_ror:2 row_mask:0xf bank_mask:0xf
	v_pk_fma_f32 v[134:135], v[162:163], v[134:135], v[136:137]
	v_cndmask_b32_e64 v137, v125, v139, s[8:9]
	v_cndmask_b32_e64 v136, v121, v138, s[8:9]
	v_cndmask_b32_e64 v139, v149, v151, s[10:11]
	v_cndmask_b32_e64 v138, v148, v150, s[10:11]
	v_pk_fma_f32 v[126:127], v[126:127], v[166:167], v[134:135]
	v_pk_mul_f32 v[138:139], v[158:159], v[138:139]
	v_pk_mul_f32 v[134:135], v[126:127], s[56:57] op_sel_hi:[1,0]
	v_pk_fma_f32 v[136:137], v[162:163], v[136:137], v[138:139]
	v_exp_f32_e32 v134, v134
	v_exp_f32_e32 v135, v135
	v_pk_fma_f32 v[136:137], v[110:111], v[166:167], v[136:137]
	v_pk_mul_f32 v[122:123], v[122:123], v[222:223] op_sel_hi:[1,0]
	v_pk_mul_f32 v[138:139], v[136:137], s[56:57] op_sel_hi:[1,0]
	v_pk_add_f32 v[134:135], v[134:135], 1.0 op_sel_hi:[1,0]
	v_exp_f32_e32 v138, v138
	v_exp_f32_e32 v139, v139
	v_rcp_f32_e32 v134, v134
	v_rcp_f32_e32 v135, v135
	s_cmp_eq_u32 s21, 0
	v_pk_add_f32 v[138:139], v[138:139], 1.0 op_sel_hi:[1,0]
	s_cselect_b64 s[28:29], -1, 0
	v_rcp_f32_e32 v138, v138
	v_rcp_f32_e32 v139, v139
	v_pk_mul_f32 v[126:127], v[126:127], v[134:135]
	s_nop 0
	v_pk_mul_f32 v[122:123], v[122:123], v[126:127]
	s_nop 0
	v_cvt_pk_bf16_f32 v125, v122, v123
	v_pk_mul_f32 v[122:123], v[136:137], v[138:139]
	s_nop 0
	v_pk_mul_f32 v[118:119], v[118:119], v[122:123]
	s_nop 0
	v_cvt_pk_bf16_f32 v121, v118, v119
	v_add_co_u32_e32 v118, vcc, 0x2000, v210
	s_nop 1
	v_addc_co_u32_e32 v119, vcc, 0, v211, vcc
	global_load_dwordx4 v[148:151], v[210:211], off offset:16
	global_load_dwordx4 v[152:155], v[118:119], off offset:3088
	v_add_co_u32_e32 v118, vcc, 0x5000, v210
	s_nop 1
	v_addc_co_u32_e32 v119, vcc, 0, v211, vcc
	global_load_dwordx4 v[156:159], v[118:119], off offset:2064
	global_load_dwordx4 v[186:189], v[210:211], off
	global_load_dwordx4 v[192:195], v[214:215], off
	global_load_dwordx4 v[180:183], v[216:217], off
	ds_read_b128 v[172:175], v2 offset:16
	ds_read_b128 v[160:163], v2 offset:528
	v_cndmask_b32_e64 v2, 0, 1, s[2:3]
	v_cmp_ne_u32_e64 s[12:13], 1, v2
	s_andn2_b64 vcc, exec, s[2:3]
	s_cbranch_vccnz .LBB0_380
	s_add_u32 s2, s59, s1
	s_addc_u32 s3, s52, s50
	v_lshl_add_u64 v[118:119], v[206:207], 2, s[2:3]
	v_add_co_u32_e32 v122, vcc, 0x2000, v118
	s_mov_b64 s[28:29], 0
	s_nop 0
	v_addc_co_u32_e32 v123, vcc, 0, v119, vcc
	global_load_dwordx4 v[168:171], v[118:119], off offset:16
	global_load_dwordx4 v[164:167], v[122:123], off offset:3088
	v_add_co_u32_e32 v122, vcc, 0x5000, v118
	s_nop 1
	v_addc_co_u32_e32 v123, vcc, 0, v119, vcc
	v_add_co_u32_e32 v118, vcc, 0x8000, v118
	s_nop 1
	v_addc_co_u32_e32 v119, vcc, 0, v119, vcc
	s_waitcnt lgkmcnt(1)
	global_load_dwordx4 v[172:175], v[122:123], off offset:2064
	s_waitcnt lgkmcnt(0)
	global_load_dwordx4 v[160:163], v[118:119], off offset:1040
	s_branch .LBB0_381

.LBB0_389:
	s_or_b64 exec, exec, s[14:15]
	v_add_u32_e32 v70, 48, v248
	v_mov_b64_e32 v[68:69], s[84:85]
	v_mad_i64_i32 v[68:69], s[14:15], v70, s62, v[68:69]
	v_lshl_add_u64 v[68:69], v[246:247], 1, v[68:69]
	v_mov_b32_e32 v242, v68
	v_mov_b32_e32 v243, v69
	ds_bpermute_b32 v232, v249, v120
	ds_bpermute_b32 v233, v249, v121
	ds_bpermute_b32 v234, v249, v122
	ds_bpermute_b32 v235, v249, v123
	s_waitcnt lgkmcnt(4)
	global_store_dwordx4 v[236:237], v[228:231], off nt
	v_mov_b32_e32 v68, v186
	v_mov_b32_e32 v69, v187
	v_mov_b32_e32 v70, v188
	v_mov_b32_e32 v71, v189
	s_nop 0
	v_mov_b32_e32 v72, v192
	v_mov_b32_e32 v73, v193
	v_mov_b32_e32 v74, v194
	v_mov_b32_e32 v75, v195
	v_mov_b32_e32 v76, v180
	v_mov_b32_e32 v77, v181
	v_mov_b32_e32 v78, v182
	v_mov_b32_e32 v79, v183
	s_and_b64 s[14:15], s[26:27], exec
	s_cselect_b32 s1, 0x800, s63
	s_add_i32 s1, s1, 0
	v_lshl_add_u32 v80, v209, 2, s1
	v_add_u32_e32 v112, 0x20000, v80
	ds_read_b128 v[92:95], v112
	ds_read_b128 v[80:83], v112 offset:512
	s_add_i32 s14, s41, 8
	s_mul_hi_i32 s1, s14, 0x2c00
	s_mulk_i32 s14, 0x2c00
	s_waitcnt lgkmcnt(1)
	v_mov_b64_e32 v[88:89], v[92:93]
	s_waitcnt lgkmcnt(0)
	v_mov_b64_e32 v[86:87], v[82:83]
	s_and_b64 vcc, exec, s[12:13]
	v_mov_b64_e32 v[84:85], v[80:81]
	v_mov_b64_e32 v[90:91], v[94:95]
	s_cbranch_vccnz .LBB0_391
	s_add_u32 s26, s59, s14
	s_addc_u32 s27, s52, s1
	v_lshl_add_u64 v[80:81], v[206:207], 2, s[26:27]
	v_add_co_u32_e32 v82, vcc, 0x2000, v80
	s_nop 1
	v_addc_co_u32_e32 v83, vcc, 0, v81, vcc
	global_load_dwordx4 v[88:91], v[80:81], off
	global_load_dwordx4 v[84:87], v[82:83], off offset:3072
	v_add_co_u32_e32 v82, vcc, 0x5000, v80
	s_nop 1
	v_addc_co_u32_e32 v83, vcc, 0, v81, vcc
	v_add_co_u32_e32 v80, vcc, 0x8000, v80
	s_nop 1
	v_addc_co_u32_e32 v81, vcc, 0, v81, vcc
	global_load_dwordx4 v[92:95], v[82:83], off offset:2048
	s_nop 0
	global_load_dwordx4 v[80:83], v[80:81], off offset:1024
	s_waitcnt vmcnt(0)
.LBB0_391:
	v_mov_b32_e32 v114, v105
	v_mov_b32_e32 v115, v106
	v_mov_b32_e32 v105, v107
	v_mov_b32_e32 v106, v101
	v_mov_b32_e32 v107, v102
	v_mov_b32_e32 v101, v103
	v_mov_b32_e32 v102, v97
	v_mov_b32_e32 v103, v98
	v_mov_b32_e32 v97, v99
	v_pk_add_f32 v[104:105], v[114:115], v[104:105]
	v_pk_add_f32 v[100:101], v[106:107], v[100:101]
	v_pk_add_f32 v[96:97], v[102:103], v[96:97]
	v_add_f32_e32 v104, v104, v105
	v_add_f32_e32 v100, v100, v101
	v_add_f32_e32 v96, v96, v97
	v_fmamk_f32 v104, v104, 0x3a800000, v241
	v_fmamk_f32 v100, v100, 0x3a800000, v241
	v_fmamk_f32 v96, v96, 0x3a800000, v241
	v_rsq_f32_e32 v104, v104
	v_rsq_f32_e32 v100, v100
	v_rsq_f32_e32 v96, v96
	v_mov_b32_e32 v209, v208
	v_pk_mul_f32 v[98:99], v[64:65], v[104:105] op_sel_hi:[1,0]
	v_pk_mul_f32 v[64:65], v[54:55], v[104:105] op_sel_hi:[1,0]
	v_pk_mul_f32 v[102:103], v[52:53], v[104:105] op_sel_hi:[1,0]
	v_pk_mul_f32 v[54:55], v[62:63], v[100:101] op_sel_hi:[1,0]
	v_pk_mul_f32 v[52:53], v[60:61], v[100:101] op_sel_hi:[1,0]
	v_pk_mul_f32 v[60:61], v[50:51], v[100:101] op_sel_hi:[1,0]
	v_pk_mul_f32 v[48:49], v[48:49], v[100:101] op_sel_hi:[1,0]
	v_pk_mul_f32 v[58:59], v[58:59], v[96:97] op_sel_hi:[1,0]
	v_pk_mul_f32 v[56:57], v[56:57], v[96:97] op_sel_hi:[1,0]
	v_pk_mul_f32 v[50:51], v[46:47], v[96:97] op_sel_hi:[1,0]
	v_pk_mul_f32 v[62:63], v[44:45], v[96:97] op_sel_hi:[1,0]
	v_cndmask_b32_e64 v44, v84, v88, s[8:9]
	v_cndmask_b32_e64 v45, v85, v89, s[8:9]
	v_cndmask_b32_e64 v88, v81, v93, s[8:9]
	v_cndmask_b32_e64 v89, v80, v92, s[8:9]
	v_mov_b32_dpp v97, v98 row_ror:2 row_mask:0xf bank_mask:0xf
	v_mov_b32_dpp v101, v99 row_ror:2 row_mask:0xf bank_mask:0xf
	v_mov_b32_dpp v92, v98 row_ror:1 row_mask:0xf bank_mask:0xf
	v_mov_b32_dpp v93, v99 row_ror:1 row_mask:0xf bank_mask:0xf
	v_cndmask_b32_e64 v45, v45, v101, s[10:11]
	v_cndmask_b32_e64 v44, v44, v97, s[10:11]
	v_pk_mul_f32 v[106:107], v[40:41], v[208:209]
	v_cndmask_b32_e64 v41, v93, v85, s[8:9]
	v_cndmask_b32_e64 v40, v92, v84, s[8:9]
	v_pk_mul_f32 v[44:45], v[68:69], v[44:45]
	v_pk_mul_f32 v[66:67], v[66:67], v[104:105] op_sel_hi:[1,0]
	v_pk_fma_f32 v[40:41], v[72:73], v[40:41], v[44:45]
	s_mov_b64 s[26:27], 0x2c10
	v_pk_fma_f32 v[40:41], v[98:99], v[76:77], v[40:41]
	s_nop 0
	v_pk_mul_f32 v[44:45], v[40:41], s[56:57] op_sel_hi:[1,0]
	s_nop 0
	v_exp_f32_e32 v44, v44
	v_exp_f32_e32 v45, v45
	v_mov_b32_dpp v99, v52 row_ror:2 row_mask:0xf bank_mask:0xf
	v_mov_b32_dpp v98, v53 row_ror:1 row_mask:0xf bank_mask:0xf
	v_cndmask_b32_e64 v84, v97, v99, s[10:11]
	v_pk_add_f32 v[44:45], v[44:45], 1.0 op_sel_hi:[1,0]
	v_mov_b32_e32 v46, v208
	v_rcp_f32_e32 v44, v44
	v_rcp_f32_e32 v45, v45
	v_mov_b32_e32 v47, v208
	v_lshl_add_u64 v[108:109], v[210:211], 0, s[26:27]
	s_mov_b64 s[26:27], 0x5810
	v_pk_mul_f32 v[40:41], v[40:41], v[44:45]
	v_cndmask_b32_e64 v45, v98, v93, s[8:9]
	v_pk_mul_f32 v[40:41], v[102:103], v[40:41]
	s_nop 0
	v_cvt_pk_bf16_f32 v40, v40, v41
	v_pk_mul_f32 v[42:43], v[42:43], v[46:47]
	v_mov_b32_dpp v102, v53 row_ror:2 row_mask:0xf bank_mask:0xf
	v_mov_b32_dpp v41, v52 row_ror:1 row_mask:0xf bank_mask:0xf
	v_cndmask_b32_e64 v85, v101, v102, s[10:11]
	v_cndmask_b32_e64 v44, v41, v92, s[8:9]
	v_pk_mul_f32 v[84:85], v[68:69], v[84:85]
	v_cndmask_b32_e64 v41, v80, v41, s[6:7]
	v_pk_fma_f32 v[44:45], v[72:73], v[44:45], v[84:85]
	v_cndmask_b32_e64 v80, v89, v99, s[6:7]
	v_pk_fma_f32 v[44:45], v[52:53], v[76:77], v[44:45]
	s_nop 0
	v_pk_mul_f32 v[84:85], v[44:45], s[56:57] op_sel_hi:[1,0]
	v_lshl_add_u64 v[110:111], v[210:211], 0, s[26:27]
	v_exp_f32_e32 v84, v84
	v_exp_f32_e32 v85, v85
	v_mov_b32_dpp v89, v57 row_ror:2 row_mask:0xf bank_mask:0xf
	s_and_b64 vcc, exec, s[12:13]
	v_pk_add_f32 v[84:85], v[84:85], 1.0 op_sel_hi:[1,0]
	s_nop 0
	v_rcp_f32_e32 v84, v84
	v_rcp_f32_e32 v85, v85
	s_nop 0
	v_pk_mul_f32 v[44:45], v[44:45], v[84:85]
	s_nop 0
	v_pk_mul_f32 v[44:45], v[48:49], v[44:45]
	s_nop 0
	v_cvt_pk_bf16_f32 v44, v44, v45
	v_cndmask_b32_e64 v45, v81, v98, s[6:7]
	v_cndmask_b32_e64 v81, v88, v102, s[6:7]
	v_mov_b32_dpp v84, v56 row_ror:1 row_mask:0xf bank_mask:0xf
	v_mov_b32_dpp v88, v56 row_ror:2 row_mask:0xf bank_mask:0xf
	v_mov_b32_dpp v85, v57 row_ror:1 row_mask:0xf bank_mask:0xf
	v_cndmask_b32_e64 v81, v81, v89, s[10:11]
	v_cndmask_b32_e64 v80, v80, v88, s[10:11]
	v_cndmask_b32_e64 v49, v85, v45, s[8:9]
	v_cndmask_b32_e64 v48, v84, v41, s[8:9]
	v_pk_mul_f32 v[80:81], v[68:69], v[80:81]
	s_nop 0
	v_pk_fma_f32 v[48:49], v[72:73], v[48:49], v[80:81]
	s_nop 0
	v_pk_fma_f32 v[48:49], v[56:57], v[76:77], v[48:49]
	v_mov_b32_dpp v41, v32 row_ror:1 row_mask:0xf bank_mask:0xf
	v_pk_mul_f32 v[56:57], v[48:49], s[56:57] op_sel_hi:[1,0]
	v_mov_b32_dpp v45, v33 row_ror:1 row_mask:0xf bank_mask:0xf
	v_exp_f32_e32 v56, v56
	v_exp_f32_e32 v57, v57
	s_nop 0
	v_pk_add_f32 v[56:57], v[56:57], 1.0 op_sel_hi:[1,0]
	s_nop 0
	v_rcp_f32_e32 v56, v56
	v_rcp_f32_e32 v57, v57
	s_nop 0
	v_pk_mul_f32 v[48:49], v[48:49], v[56:57]
	s_nop 0
	v_pk_mul_f32 v[48:49], v[62:63], v[48:49]
	s_nop 0
	v_cvt_pk_bf16_f32 v48, v48, v49
	v_cndmask_b32_e64 v57, v45, v85, s[8:9]
	v_mov_b32_dpp v62, v33 row_ror:2 row_mask:0xf bank_mask:0xf
	v_mov_b32_dpp v49, v32 row_ror:2 row_mask:0xf bank_mask:0xf
	v_cndmask_b32_e64 v63, v89, v62, s[10:11]
	v_cndmask_b32_e64 v62, v88, v49, s[10:11]
	v_cndmask_b32_e64 v56, v41, v84, s[8:9]
	v_pk_mul_f32 v[62:63], v[68:69], v[62:63]
	v_cndmask_b32_e64 v41, v86, v90, s[8:9]
	v_pk_fma_f32 v[56:57], v[72:73], v[56:57], v[62:63]
	v_cndmask_b32_e64 v45, v87, v91, s[8:9]
	v_pk_fma_f32 v[56:57], v[32:33], v[76:77], v[56:57]
	s_nop 0
	v_pk_mul_f32 v[62:63], v[56:57], s[56:57] op_sel_hi:[1,0]
	s_nop 0
	v_exp_f32_e32 v62, v62
	v_exp_f32_e32 v63, v63
	v_mov_b32_dpp v76, v66 row_ror:2 row_mask:0xf bank_mask:0xf
	v_pk_add_f32 v[62:63], v[62:63], 1.0 op_sel_hi:[1,0]
	v_mov_b32_dpp v77, v67 row_ror:2 row_mask:0xf bank_mask:0xf
	v_rcp_f32_e32 v62, v62
	v_rcp_f32_e32 v63, v63
	v_mov_b32_dpp v72, v66 row_ror:1 row_mask:0xf bank_mask:0xf
	v_mov_b32_dpp v73, v67 row_ror:1 row_mask:0xf bank_mask:0xf
	v_cndmask_b32_e64 v69, v45, v77, s[10:11]
	v_cndmask_b32_e64 v68, v41, v76, s[10:11]
	v_pk_mul_f32 v[56:57], v[56:57], v[62:63]
	v_cndmask_b32_e64 v63, v73, v87, s[8:9]
	v_cndmask_b32_e64 v62, v72, v86, s[8:9]
	v_pk_mul_f32 v[68:69], v[70:71], v[68:69]
	v_pk_mul_f32 v[56:57], v[106:107], v[56:57]
	v_pk_fma_f32 v[62:63], v[74:75], v[62:63], v[68:69]
	s_nop 0
	v_pk_fma_f32 v[62:63], v[66:67], v[78:79], v[62:63]
	s_nop 0
	v_pk_mul_f32 v[66:67], v[62:63], s[56:57] op_sel_hi:[1,0]
	v_mov_b32_dpp v68, v54 row_ror:2 row_mask:0xf bank_mask:0xf
	v_exp_f32_e32 v66, v66
	v_exp_f32_e32 v67, v67
	v_mov_b32_dpp v69, v55 row_ror:2 row_mask:0xf bank_mask:0xf
	v_cvt_pk_bf16_f32 v56, v56, v57
	v_cndmask_b32_e64 v49, v83, v95, s[8:9]
	v_pk_add_f32 v[66:67], v[66:67], 1.0 op_sel_hi:[1,0]
	v_cndmask_b32_e64 v57, v82, v94, s[8:9]
	v_rcp_f32_e32 v66, v66
	v_rcp_f32_e32 v67, v67
	v_cndmask_b32_e64 v57, v57, v68, s[6:7]
	v_cndmask_b32_e64 v49, v49, v69, s[6:7]
	v_pk_mul_f32 v[62:63], v[62:63], v[66:67]
	s_nop 0
	v_pk_mul_f32 v[62:63], v[64:65], v[62:63]
	v_mov_b32_dpp v66, v54 row_ror:1 row_mask:0xf bank_mask:0xf
	v_mov_b32_dpp v67, v55 row_ror:1 row_mask:0xf bank_mask:0xf
	v_cndmask_b32_e64 v65, v77, v69, s[10:11]
	v_cndmask_b32_e64 v64, v76, v68, s[10:11]
	v_cvt_pk_bf16_f32 v41, v62, v63
	v_cndmask_b32_e64 v63, v67, v73, s[8:9]
	v_cndmask_b32_e64 v62, v66, v72, s[8:9]
	v_pk_mul_f32 v[64:65], v[70:71], v[64:65]
	s_nop 0
	v_pk_fma_f32 v[62:63], v[74:75], v[62:63], v[64:65]
	s_nop 0
	v_pk_fma_f32 v[62:63], v[54:55], v[78:79], v[62:63]
	s_nop 0
	v_pk_mul_f32 v[64:65], v[62:63], s[56:57] op_sel_hi:[1,0]
	s_nop 0
	v_exp_f32_e32 v64, v64
	v_exp_f32_e32 v65, v65
	s_nop 0
	v_pk_add_f32 v[64:65], v[64:65], 1.0 op_sel_hi:[1,0]
	s_nop 0
	v_rcp_f32_e32 v64, v64
	v_rcp_f32_e32 v65, v65
	s_nop 0
	v_pk_mul_f32 v[62:63], v[62:63], v[64:65]
	s_nop 0
	v_pk_mul_f32 v[60:61], v[60:61], v[62:63]
	s_nop 0
	v_cvt_pk_bf16_f32 v45, v60, v61
	v_cndmask_b32_e64 v60, v82, v66, s[6:7]
	v_cndmask_b32_e64 v61, v83, v67, s[6:7]
	v_mov_b32_dpp v66, v58 row_ror:2 row_mask:0xf bank_mask:0xf
	v_mov_b32_dpp v67, v59 row_ror:2 row_mask:0xf bank_mask:0xf
	v_mov_b32_dpp v64, v58 row_ror:1 row_mask:0xf bank_mask:0xf
	v_mov_b32_dpp v65, v59 row_ror:1 row_mask:0xf bank_mask:0xf
	v_cndmask_b32_e64 v63, v49, v67, s[10:11]
	v_cndmask_b32_e64 v62, v57, v66, s[10:11]
	v_cndmask_b32_e64 v61, v65, v61, s[8:9]
	v_cndmask_b32_e64 v60, v64, v60, s[8:9]
	v_pk_mul_f32 v[62:63], v[70:71], v[62:63]
	s_nop 0
	v_pk_fma_f32 v[60:61], v[74:75], v[60:61], v[62:63]
	s_nop 0
	v_pk_fma_f32 v[58:59], v[58:59], v[78:79], v[60:61]
	v_mov_b32_dpp v57, v34 row_ror:2 row_mask:0xf bank_mask:0xf
	v_pk_mul_f32 v[60:61], v[58:59], s[56:57] op_sel_hi:[1,0]
	s_nop 0
	v_exp_f32_e32 v60, v60
	v_exp_f32_e32 v61, v61
	s_nop 0
	v_pk_add_f32 v[60:61], v[60:61], 1.0 op_sel_hi:[1,0]
	s_nop 0
	v_rcp_f32_e32 v60, v60
	v_rcp_f32_e32 v61, v61
	s_nop 0
	v_pk_mul_f32 v[58:59], v[58:59], v[60:61]
	s_nop 0
	v_pk_mul_f32 v[50:51], v[50:51], v[58:59]
	s_nop 0
	v_cvt_pk_bf16_f32 v49, v50, v51
	v_mov_b32_dpp v58, v35 row_ror:2 row_mask:0xf bank_mask:0xf
	v_mov_b32_dpp v50, v34 row_ror:1 row_mask:0xf bank_mask:0xf
	v_mov_b32_dpp v51, v35 row_ror:1 row_mask:0xf bank_mask:0xf
	v_cndmask_b32_e64 v59, v67, v58, s[10:11]
	v_cndmask_b32_e64 v58, v66, v57, s[10:11]
	v_cndmask_b32_e64 v51, v51, v65, s[8:9]
	v_cndmask_b32_e64 v50, v50, v64, s[8:9]
	v_pk_mul_f32 v[58:59], v[70:71], v[58:59]
	s_nop 0
	v_pk_fma_f32 v[50:51], v[74:75], v[50:51], v[58:59]
	s_nop 0
	v_pk_fma_f32 v[50:51], v[34:35], v[78:79], v[50:51]
	s_nop 0
	v_pk_mul_f32 v[58:59], v[50:51], s[56:57] op_sel_hi:[1,0]
	s_nop 0
	v_exp_f32_e32 v58, v58
	v_exp_f32_e32 v59, v59
	s_nop 0
	v_pk_add_f32 v[58:59], v[58:59], 1.0 op_sel_hi:[1,0]
	s_nop 0
	v_rcp_f32_e32 v58, v58
	v_rcp_f32_e32 v59, v59
	s_nop 0
	v_pk_mul_f32 v[50:51], v[50:51], v[58:59]
	s_nop 0
	v_pk_mul_f32 v[42:43], v[42:43], v[50:51]
	s_nop 0
	v_cvt_pk_bf16_f32 v57, v42, v43
	global_load_dwordx4 v[58:61], v[210:211], off offset:16
	global_load_dwordx4 v[62:65], v[108:109], off
	global_load_dwordx4 v[66:69], v[110:111], off
	ds_read_b128 v[78:81], v112 offset:16
	ds_read_b128 v[70:73], v112 offset:528
	s_waitcnt lgkmcnt(1)
	v_mov_b64_e32 v[84:85], v[80:81]
	s_waitcnt lgkmcnt(0)
	v_mov_b64_e32 v[76:77], v[72:73]
	v_mov_b64_e32 v[74:75], v[70:71]
	v_mov_b64_e32 v[82:83], v[78:79]
	s_cbranch_vccnz .LBB0_393
	s_add_u32 s12, s59, s14
	s_addc_u32 s13, s52, s1
	v_lshl_add_u64 v[42:43], v[206:207], 2, s[12:13]
	v_add_co_u32_e32 v50, vcc, 0x2000, v42
	s_nop 1
	v_addc_co_u32_e32 v51, vcc, 0, v43, vcc
	global_load_dwordx4 v[82:85], v[42:43], off offset:16
	global_load_dwordx4 v[74:77], v[50:51], off offset:3088
	v_add_co_u32_e32 v50, vcc, 0x5000, v42
	s_nop 1
	v_addc_co_u32_e32 v51, vcc, 0, v43, vcc
	v_add_co_u32_e32 v42, vcc, 0x8000, v42
	s_nop 1
	v_addc_co_u32_e32 v43, vcc, 0, v43, vcc
	global_load_dwordx4 v[78:81], v[50:51], off offset:2064
	global_load_dwordx4 v[70:73], v[42:43], off offset:1040
